# speedup vs baseline: 1.0291x; 1.0071x over previous
; #define SBAR() __builtin_amdgcn_sched_barrier(0)
; template <bool ALIBI, bool LAST>
; DEVI void softmax_tile(f32x16& p0, f32x16& p1, const float C, const float nslope2, const float dbase, float& m_reg, float& l_reg, float& alpha,
;                        bf16x8& pa0, bf16x8& pa1, bf16x8& pa2, bf16x8& pa3) {
;   if constexpr (ALIBI) {
; #pragma unroll
;     for (int r = 0; r < 16; ++r) {
;       const float c = (float)((r & 3) + 8 * (r >> 2));
;       p0[r] = fmaf(nslope2, fabsf(dbase - c), p0[r]);
;       p1[r] = fmaf(nslope2, fabsf(dbase - (c + 32.f)), p1[r]);
;     }
;   }
; template <int DQK, bool ALIBI>
; DEVI void attn_pass(const AttnArgs& a, f32x16 (&o)[4], const int tid_) {
;     ...
;       if constexpr (DQK == 128 || DQK == 64 || DQK == 192) {
;         constexpr int NG4 = DQK / 64;
;         bf16x8 ka[4][2], kb[4][2];
; #pragma unroll
;         for (int s = 0; s < 4; ++s) { ka[s][0] = *(const bf16x8*)(Ks + KCB(s)); ka[s][1] = *(const bf16x8*)(Ks + 32 * KPITCH + KCB(s)); }
;         SBAR();
; #pragma unroll
;         for (int g = 0; g < NG4; ++g) {
;           if (g + 1 < NG4) {
; #pragma unroll
;             for (int s = 0; s < 4; ++s) { const int d1 = (g + 1) * 4 + s;
;               if (g & 1) { ka[s][0] = *(const bf16x8*)(Ks + KCB(d1)); ka[s][1] = *(const bf16x8*)(Ks + 32 * KPITCH + KCB(d1)); }
;               else       { kb[s][0] = *(const bf16x8*)(Ks + KCB(d1)); kb[s][1] = *(const bf16x8*)(Ks + 32 * KPITCH + KCB(d1)); } }
;           }
; #pragma unroll
;           for (int s = 0; s < 4; ++s) { const int d0 = g * 4 + s;
;             p0 = __builtin_amdgcn_mfma_f32_32x32x16_bf16((g & 1) ? kb[s][0] : ka[s][0], qr[d0], p0, 0, 0, 0);
;             p1 = __builtin_amdgcn_mfma_f32_32x32x16_bf16((g & 1) ? kb[s][1] : ka[s][1], qr[d0], p1, 0, 0, 0); }
;           SBAR();
.LBB0_186:
	s_and_saveexec_b64 s[62:63], s[4:5]
	s_cbranch_execz .LBB0_192
	v_lshl_add_u32 v0, s50, 13, v190
	v_add_u32_e32 v6, v0, v198
	v_add_u32_e32 v14, v0, v199
	ds_read_b128 v[2:5], v6 offset:32768
	ds_read_b128 v[6:9], v6 offset:36864
	ds_read_b128 v[10:13], v14 offset:32768
	ds_read_b128 v[128:131], v14 offset:36864
	v_add_u32_e32 v14, v0, v200
	v_add_u32_e32 v0, v0, v201
	ds_read_b128 v[206:209], v14 offset:32768
	ds_read_b128 v[210:213], v14 offset:36864
	ds_read_b128 v[214:217], v0 offset:32768
	ds_read_b128 v[218:221], v0 offset:36864
	s_add_i32 s37, s60, s66
	s_cmp_gt_i32 s66, s45
	s_cselect_b32 vcc_lo, s84, s37
	s_cmp_eq_u32 vcc_lo, s84
	s_waitcnt lgkmcnt(6)
	v_mfma_f32_32x32x16_bf16 v[80:95], v[2:5], v[112:115], 0
	v_mfma_f32_32x32x16_bf16 v[96:111], v[6:9], v[112:115], 0
	s_waitcnt lgkmcnt(4)
	v_mfma_f32_32x32x16_bf16 v[80:95], v[10:13], v[116:119], v[80:95]
	v_mfma_f32_32x32x16_bf16 v[96:111], v[128:131], v[116:119], v[96:111]
	s_waitcnt lgkmcnt(2)
	v_mfma_f32_32x32x16_bf16 v[80:95], v[206:209], v[120:123], v[80:95]
	v_mfma_f32_32x32x16_bf16 v[96:111], v[210:213], v[120:123], v[96:111]
	s_waitcnt lgkmcnt(0)
	v_mfma_f32_32x32x16_bf16 v[80:95], v[214:217], v[124:127], v[80:95]
	v_mfma_f32_32x32x16_bf16 v[96:111], v[218:221], v[124:127], v[96:111]
	s_mov_b64 s[66:67], -1
	v_max_f32_e32 v205, v204, v204
	s_cbranch_scc1 .LBB0_194
	s_lshl_b32 s37, vcc_lo, 6
	s_or_b32 s37, s37, 16
	v_cvt_f32_i32_e32 v0, s37
	v_sub_f32_e32 v0, v184, v0
	v_cmp_le_f32_e32 vcc, 0x426c0000, v0
	s_cmp_eq_u64 vcc, exec
	s_cbranch_scc1 .Lmy_C_pos
	v_cmp_ge_f32_e32 vcc, 0, v0
	s_cmp_eq_u64 vcc, exec
	s_cbranch_scc1 .Lmy_C_neg
	v_mov_b32_e32 v131, 0
	v_add_f32_e32 v14, 0xc1200000, v0
	v_add_f32_e32 v3, 0xc2000000, v0
	s_nop 1
	v_fma_f32 v15, v182, |v14|, v86
	v_add_f32_e32 v14, 0xc2280000, v0
	v_fma_f32 v3, v182, |v3|, v96
	v_add_f32_e32 v5, 0xc2040000, v0
	v_fma_f32 v96, v182, |v14|, v102
	v_add_f32_e32 v14, 0xc1300000, v0
	v_fma_f32 v5, v182, |v5|, v97
	v_add_f32_e32 v7, 0xc2080000, v0
	v_fma_f32 v97, v182, |v14|, v87
	v_add_f32_e32 v14, 0xc22c0000, v0
	v_fma_f32 v7, v182, |v7|, v98
	v_fma_f32 v98, v182, |v14|, v103
	v_add_f32_e32 v14, 0xc1800000, v0
	v_add_f32_e32 v9, 0xc20c0000, v0
	v_fma_f32 v88, v182, |v14|, v88
	v_add_f32_e32 v14, 0xc2400000, v0
	v_fma_f32 v9, v182, |v9|, v99
	v_fma_f32 v99, v182, |v14|, v104
	v_add_f32_e32 v14, 0xc1880000, v0
	v_add_f32_e32 v11, 0xc2200000, v0
	v_fma_f32 v89, v182, |v14|, v89
	v_add_f32_e32 v14, 0xc2440000, v0
	v_fma_f32 v11, v182, |v11|, v100
	v_fma_f32 v100, v182, |v14|, v105
	v_add_f32_e32 v14, 0xc1900000, v0
	v_add_f32_e32 v13, 0xc2240000, v0
	v_fma_f32 v90, v182, |v14|, v90
	v_add_f32_e32 v14, 0xc2480000, v0
	v_fma_f32 v13, v182, |v13|, v101
	v_fma_f32 v101, v182, |v14|, v106
	v_add_f32_e32 v14, 0xc1980000, v0
	v_fma_f32 v91, v182, |v14|, v91
	v_add_f32_e32 v14, 0xc24c0000, v0
	v_fma_f32 v102, v182, |v14|, v107
	v_add_f32_e32 v14, 0xc1c00000, v0
	v_fma_f32 v92, v182, |v14|, v92
	v_add_f32_e32 v14, 0xc2600000, v0
	v_fma_f32 v103, v182, |v14|, v108
	v_add_f32_e32 v14, 0xc1c80000, v0
	v_fma_f32 v93, v182, |v14|, v93
	v_add_f32_e32 v14, 0xc2640000, v0
	v_fma_f32 v104, v182, |v14|, v109
	v_add_f32_e32 v14, 0xc1d00000, v0
	v_add_f32_e32 v4, -1.0, v0
	v_fma_f32 v94, v182, |v14|, v94
	v_add_f32_e32 v14, 0xc2680000, v0
	v_fma_f32 v2, v182, |v0|, v80
	v_fma_f32 v4, v182, |v4|, v81
	v_add_f32_e32 v6, -2.0, v0
	v_add_f32_e32 v8, 0xc0400000, v0
	v_add_f32_e32 v10, 0xc1000000, v0
	v_add_f32_e32 v12, 0xc1100000, v0
	v_fma_f32 v105, v182, |v14|, v110
	v_add_f32_e32 v14, 0xc1d80000, v0
	v_add_f32_e32 v0, 0xc26c0000, v0
	v_fma_f32 v6, v182, |v6|, v82
	v_fma_f32 v8, v182, |v8|, v83
	v_fma_f32 v106, v182, |v0|, v111
	v_max_f32_e32 v0, v2, v4
	v_fma_f32 v10, v182, |v10|, v84
	v_fma_f32 v12, v182, |v12|, v85
	v_max3_f32 v0, v0, v6, v8
	v_max3_f32 v0, v0, v10, v12
	v_max3_f32 v0, v0, v15, v97
	v_max3_f32 v0, v0, v88, v89
	v_max3_f32 v0, v0, v90, v91
	v_fma_f32 v95, v182, |v14|, v95

; #define SBAR() __builtin_amdgcn_sched_barrier(0)
; template <bool ALIBI, bool LAST>
; DEVI void softmax_tile(f32x16& p0, f32x16& p1, const float C, const float nslope2, const float dbase, float& m_reg, float& l_reg, float& alpha,
;                        bf16x8& pa0, bf16x8& pa1, bf16x8& pa2, bf16x8& pa3) {
;     ...
;   float pmax = p0[0];
; #pragma unroll
;   for (int r = 1; r < 16; ++r) pmax = fmaxf(pmax, p0[r]);
;   if constexpr (!LAST) {
; #pragma unroll
;     for (int r = 0; r < 16; ++r) pmax = fmaxf(pmax, p1[r]);
;   }
;   { auto rr = __builtin_amdgcn_permlane32_swap(__float_as_uint(pmax), __float_as_uint(pmax), false, false);
;     pmax = fmaxf(__uint_as_float(rr[0]), __uint_as_float(rr[1])); }
;   const float THRU = 8.f * LOG2E / C;
;   const float CU = C;
;   if (__builtin_expect(__all(pmax - m_reg <= THRU), 1)) { alpha = 1.f; }
;   else { float mn = fmaxf(m_reg, pmax); alpha = __builtin_amdgcn_exp2f((m_reg - mn) * CU); m_reg = mn; }
; template <int DQK, bool ALIBI>
; DEVI void attn_pass(const AttnArgs& a, f32x16 (&o)[4], const int tid_) {
;     ...
;     if (wactive) {
;       f32x16 p0 = f32x16{}, p1 = f32x16{};
;       const unsigned char* Ks = K_lds + buf * SHM_K + r32 * KPITCH;
;       const int key = KKEY(r32);
;     ...
;       if constexpr (DQK == 128 || DQK == 64 || DQK == 192) {
;         constexpr int NG4 = DQK / 64;
;         bf16x8 ka[4][2], kb[4][2];
; #pragma unroll
;         for (int s = 0; s < 4; ++s) { ka[s][0] = *(const bf16x8*)(Ks + KCB(s)); ka[s][1] = *(const bf16x8*)(Ks + 32 * KPITCH + KCB(s)); }
;         SBAR();
; #pragma unroll
;         for (int g = 0; g < NG4; ++g) {
;           if (g + 1 < NG4) {
; #pragma unroll
;             for (int s = 0; s < 4; ++s) { const int d1 = (g + 1) * 4 + s;
;               if (g & 1) { ka[s][0] = *(const bf16x8*)(Ks + KCB(d1)); ka[s][1] = *(const bf16x8*)(Ks + 32 * KPITCH + KCB(d1)); }
;               else       { kb[s][0] = *(const bf16x8*)(Ks + KCB(d1)); kb[s][1] = *(const bf16x8*)(Ks + 32 * KPITCH + KCB(d1)); } }
;           }
; #pragma unroll
;           for (int s = 0; s < 4; ++s) { const int d0 = g * 4 + s;
;             p0 = __builtin_amdgcn_mfma_f32_32x32x16_bf16((g & 1) ? kb[s][0] : ka[s][0], qr[d0], p0, 0, 0, 0);
;             p1 = __builtin_amdgcn_mfma_f32_32x32x16_bf16((g & 1) ? kb[s][1] : ka[s][1], qr[d0], p1, 0, 0, 0); }
;           SBAR();
.LBB0_216:
	s_and_saveexec_b64 s[34:35], s[4:5]
	s_cbranch_execz .LBB0_210
	s_mul_i32 s13, s42, 0x6000
	v_add_u32_e32 v74, s13, v198
	v_add_u32_e32 v168, v74, v202
	v_add_u32_e32 v169, v74, v203
	v_add_u32_e32 v240, v74, v200
	v_add_u32_e32 v241, v74, v201
	ds_read_b128 v[66:69], v168 offset:32768
	ds_read_b128 v[70:73], v168 offset:45056
	ds_read_b128 v[204:207], v169 offset:32768
	ds_read_b128 v[208:211], v169 offset:45056
	ds_read_b128 v[212:215], v240 offset:32768
	ds_read_b128 v[216:219], v240 offset:45056
	ds_read_b128 v[220:223], v241 offset:32768
	ds_read_b128 v[224:227], v241 offset:45056
	s_waitcnt lgkmcnt(6)
	v_mfma_f32_32x32x16_bf16 v[82:97], v[66:69], v[126:129], 0
	v_mfma_f32_32x32x16_bf16 v[66:81], v[70:73], v[126:129], 0
	s_waitcnt lgkmcnt(4)
	v_mfma_f32_32x32x16_bf16 v[82:97], v[204:207], v[122:125], v[82:97]
	v_mfma_f32_32x32x16_bf16 v[66:81], v[208:211], v[122:125], v[66:81]
	s_waitcnt lgkmcnt(2)
	v_mfma_f32_32x32x16_bf16 v[82:97], v[212:215], v[118:121], v[82:97]
	v_mfma_f32_32x32x16_bf16 v[66:81], v[216:219], v[118:121], v[66:81]
	s_waitcnt lgkmcnt(0)
	v_mfma_f32_32x32x16_bf16 v[82:97], v[220:223], v[114:117], v[82:97]
	ds_read_b128 v[204:207], v168 offset:32896
	ds_read_b128 v[208:211], v168 offset:45184
	ds_read_b128 v[212:215], v169 offset:32896
	ds_read_b128 v[216:219], v169 offset:45184
	ds_read_b128 v[220:223], v240 offset:32896
	ds_read_b128 v[228:231], v240 offset:45184
	ds_read_b128 v[232:235], v241 offset:32896
	ds_read_b128 v[236:239], v241 offset:45184
	v_mfma_f32_32x32x16_bf16 v[66:81], v[224:227], v[114:117], v[66:81]
	s_waitcnt lgkmcnt(6)
	v_mfma_f32_32x32x16_bf16 v[82:97], v[204:207], v[110:113], v[82:97]
	v_mfma_f32_32x32x16_bf16 v[66:81], v[208:211], v[110:113], v[66:81]
	s_waitcnt lgkmcnt(4)
	v_mfma_f32_32x32x16_bf16 v[82:97], v[212:215], v[106:109], v[82:97]
	v_mfma_f32_32x32x16_bf16 v[66:81], v[216:219], v[106:109], v[66:81]
	s_waitcnt lgkmcnt(2)
	v_mfma_f32_32x32x16_bf16 v[82:97], v[220:223], v[102:105], v[82:97]
	v_mfma_f32_32x32x16_bf16 v[66:81], v[228:231], v[102:105], v[66:81]
	s_waitcnt lgkmcnt(0)
	v_mfma_f32_32x32x16_bf16 v[82:97], v[232:235], v[98:101], v[82:97]
	ds_read_b128 v[204:207], v168 offset:33024
	ds_read_b128 v[208:211], v168 offset:45312
	ds_read_b128 v[212:215], v169 offset:33024
	ds_read_b128 v[216:219], v169 offset:45312
	ds_read_b128 v[220:223], v240 offset:33024
	ds_read_b128 v[224:227], v240 offset:45312
	ds_read_b128 v[228:231], v241 offset:33024
	ds_read_b128 v[232:235], v241 offset:45312
	v_mfma_f32_32x32x16_bf16 v[66:81], v[236:239], v[98:101], v[66:81]
	s_waitcnt lgkmcnt(6)
	v_mfma_f32_32x32x16_bf16 v[82:97], v[204:207], v[134:137], v[82:97]
	v_mfma_f32_32x32x16_bf16 v[66:81], v[208:211], v[134:137], v[66:81]
	s_waitcnt lgkmcnt(4)
	v_mfma_f32_32x32x16_bf16 v[82:97], v[212:215], v[142:145], v[82:97]
	v_mfma_f32_32x32x16_bf16 v[66:81], v[216:219], v[142:145], v[66:81]
	s_waitcnt lgkmcnt(2)
	v_mfma_f32_32x32x16_bf16 v[82:97], v[220:223], v[130:133], v[82:97]
	v_mfma_f32_32x32x16_bf16 v[66:81], v[224:227], v[130:133], v[66:81]
	s_waitcnt lgkmcnt(0)
	v_mfma_f32_32x32x16_bf16 v[82:97], v[228:231], v[138:141], v[82:97]
	v_mfma_f32_32x32x16_bf16 v[66:81], v[232:235], v[138:141], v[66:81]
	v_lshl_add_u32 v236, s42, 14, v196
	ds_read_b64_tr_b16 v[204:205], v236 offset:0x0
	ds_read_b64_tr_b16 v[206:207], v236 offset:0x800
	ds_read_b64_tr_b16 v[208:209], v236 offset:0x200
	ds_read_b64_tr_b16 v[210:211], v236 offset:0xa00
	ds_read_b64_tr_b16 v[212:213], v236 offset:0x400
	ds_read_b64_tr_b16 v[214:215], v236 offset:0xc00
	ds_read_b64_tr_b16 v[216:217], v236 offset:0x600
	ds_read_b64_tr_b16 v[218:219], v236 offset:0xe00
	s_nop 1
	v_max3_f32 v168, v82, v83, v84
	v_max3_f32 v168, v168, v85, v86
	v_max3_f32 v168, v168, v87, v88
	v_max3_f32 v168, v168, v89, v90
	v_max3_f32 v168, v168, v91, v92
	v_max3_f32 v168, v168, v93, v94
	v_max3_f32 v168, v168, v95, v96
	v_max3_f32 v168, v168, v97, v66
	v_max3_f32 v168, v168, v67, v68
	v_max3_f32 v168, v168, v69, v70
	v_max3_f32 v168, v168, v71, v72
	v_max3_f32 v168, v168, v73, v74
	v_max3_f32 v168, v168, v75, v76
	v_max3_f32 v168, v168, v77, v78
	v_max3_f32 v168, v168, v79, v80
	v_max_f32_e32 v168, v168, v81
	v_mov_b32_e32 v169, v168
	s_nop 1
	v_permlane32_swap_b32_e32 v168, v169
	v_max_f32_e32 v168, v168, v169
	v_sub_f32_e32 v169, v168, v199
	v_cmp_ge_f32_e32 vcc, s17, v169
	s_cmp_eq_u64 vcc, exec
	s_cbranch_scc0 .Lmy_B_slow
	v_mov_b32_e32 v168, 1.0

; #define SBAR() __builtin_amdgcn_sched_barrier(0)
; template <bool ALIBI, bool LAST>
; DEVI void softmax_tile(f32x16& p0, f32x16& p1, const float C, const float nslope2, const float dbase, float& m_reg, float& l_reg, float& alpha,
;                        bf16x8& pa0, bf16x8& pa1, bf16x8& pa2, bf16x8& pa3) {
;     ...
;   float pmax = p0[0];
; #pragma unroll
;   for (int r = 1; r < 16; ++r) pmax = fmaxf(pmax, p0[r]);
;   if constexpr (!LAST) {
; #pragma unroll
;     for (int r = 0; r < 16; ++r) pmax = fmaxf(pmax, p1[r]);
;   }
;   { auto rr = __builtin_amdgcn_permlane32_swap(__float_as_uint(pmax), __float_as_uint(pmax), false, false);
;     pmax = fmaxf(__uint_as_float(rr[0]), __uint_as_float(rr[1])); }
;   const float THRU = 8.f * LOG2E / C;
;   const float CU = C;
;   if (__builtin_expect(__all(pmax - m_reg <= THRU), 1)) { alpha = 1.f; }
;   else { float mn = fmaxf(m_reg, pmax); alpha = __builtin_amdgcn_exp2f((m_reg - mn) * CU); m_reg = mn; }
; template <int DQK, bool ALIBI>
; DEVI void attn_pass(const AttnArgs& a, f32x16 (&o)[4], const int tid_) {
;     ...
;       const unsigned char* Ks = K_lds + buf * SHM_K + r32 * KPITCH;
;       const int key = KKEY(r32);
;     ...
;       if constexpr (DQK == 128 || DQK == 64 || DQK == 192) {
;         constexpr int NG4 = DQK / 64;
;         bf16x8 ka[4][2], kb[4][2];
; #pragma unroll
;         for (int s = 0; s < 4; ++s) { ka[s][0] = *(const bf16x8*)(Ks + KCB(s)); ka[s][1] = *(const bf16x8*)(Ks + 32 * KPITCH + KCB(s)); }
;         SBAR();
; #pragma unroll
;         for (int g = 0; g < NG4; ++g) {
;           if (g + 1 < NG4) {
; #pragma unroll
;             for (int s = 0; s < 4; ++s) { const int d1 = (g + 1) * 4 + s;
;               if (g & 1) { ka[s][0] = *(const bf16x8*)(Ks + KCB(d1)); ka[s][1] = *(const bf16x8*)(Ks + 32 * KPITCH + KCB(d1)); }
;               else       { kb[s][0] = *(const bf16x8*)(Ks + KCB(d1)); kb[s][1] = *(const bf16x8*)(Ks + 32 * KPITCH + KCB(d1)); } }
;           }
; #pragma unroll
;           for (int s = 0; s < 4; ++s) { const int d0 = g * 4 + s;
;             p0 = __builtin_amdgcn_mfma_f32_32x32x16_bf16((g & 1) ? kb[s][0] : ka[s][0], qr[d0], p0, 0, 0, 0);
;             p1 = __builtin_amdgcn_mfma_f32_32x32x16_bf16((g & 1) ? kb[s][1] : ka[s][1], qr[d0], p1, 0, 0, 0); }
;           SBAR();
.LBB0_233:
	s_and_saveexec_b64 s[12:13], s[4:5]
	s_cbranch_execz .LBB0_227
	s_lshl_b32 s34, s34, 14
	v_add_u32_e32 v144, s34, v148
	v_add_u32_e32 v70, v144, v158
	v_add_u32_e32 v74, v144, v159
	ds_read_b128 v[66:69], v70 offset:32768
	ds_read_b128 v[70:73], v70 offset:40960
	ds_read_b128 v[160:163], v74 offset:32768
	ds_read_b128 v[164:167], v74 offset:40960
	v_add_u32_e32 v74, v144, v156
	ds_read_b128 v[184:187], v74 offset:32768
	ds_read_b128 v[188:191], v74 offset:40960
	v_add_u32_e32 v74, v144, v157
	ds_read_b128 v[192:195], v74 offset:32768
	ds_read_b128 v[196:199], v74 offset:40960
	s_waitcnt lgkmcnt(6)
	v_mfma_f32_32x32x16_bf16 v[82:97], v[66:69], v[126:129], 0
	v_add_u32_e32 v168, v144, v153
	v_mfma_f32_32x32x16_bf16 v[66:81], v[70:73], v[126:129], 0
	s_waitcnt lgkmcnt(4)
	v_mfma_f32_32x32x16_bf16 v[82:97], v[160:163], v[122:125], v[82:97]
	v_mfma_f32_32x32x16_bf16 v[66:81], v[164:167], v[122:125], v[66:81]
	v_add_u32_e32 v164, v144, v155
	ds_read_b128 v[160:163], v164 offset:32768
	ds_read_b128 v[164:167], v164 offset:40960
	s_waitcnt lgkmcnt(4)
	v_mfma_f32_32x32x16_bf16 v[82:97], v[184:187], v[118:121], v[82:97]
	v_mfma_f32_32x32x16_bf16 v[66:81], v[188:191], v[118:121], v[66:81]
	ds_read_b128 v[184:187], v168 offset:32768
	ds_read_b128 v[188:191], v168 offset:40960
	v_add_u32_e32 v168, v144, v152
	v_add_u32_e32 v144, v144, v154
	s_waitcnt lgkmcnt(4)
	v_mfma_f32_32x32x16_bf16 v[82:97], v[192:195], v[114:117], v[82:97]
	ds_read_b128 v[192:195], v168 offset:32768
	ds_read_b128 v[200:203], v168 offset:40960
	ds_read_b128 v[204:207], v144 offset:32768
	ds_read_b128 v[208:211], v144 offset:40960
	v_mfma_f32_32x32x16_bf16 v[66:81], v[196:199], v[114:117], v[66:81]
	s_waitcnt lgkmcnt(0)
	v_mfma_f32_32x32x16_bf16 v[82:97], v[160:163], v[110:113], v[82:97]
	v_mfma_f32_32x32x16_bf16 v[66:81], v[164:167], v[110:113], v[66:81]
	v_mfma_f32_32x32x16_bf16 v[82:97], v[184:187], v[106:109], v[82:97]
	v_mfma_f32_32x32x16_bf16 v[66:81], v[188:191], v[106:109], v[66:81]
	v_mfma_f32_32x32x16_bf16 v[82:97], v[192:195], v[102:105], v[82:97]
	v_mfma_f32_32x32x16_bf16 v[66:81], v[200:203], v[102:105], v[66:81]
	v_mfma_f32_32x32x16_bf16 v[82:97], v[204:207], v[98:101], v[82:97]
	v_mfma_f32_32x32x16_bf16 v[66:81], v[208:211], v[98:101], v[66:81]
	v_add_u32_e32 v211, s34, v145
	ds_read_b64_tr_b16 v[192:193], v211 offset:0x0
	ds_read_b64_tr_b16 v[194:195], v211 offset:0x800
	ds_read_b64_tr_b16 v[196:197], v211 offset:0x200
	ds_read_b64_tr_b16 v[198:199], v211 offset:0xa00
	ds_read_b64_tr_b16 v[200:201], v211 offset:0x400
	ds_read_b64_tr_b16 v[202:203], v211 offset:0xc00
	ds_read_b64_tr_b16 v[204:205], v211 offset:0x600
	ds_read_b64_tr_b16 v[206:207], v211 offset:0xe00
	s_nop 1
	v_max3_f32 v144, v82, v83, v84
	v_max3_f32 v144, v144, v85, v86
	v_max3_f32 v144, v144, v87, v88
	v_max3_f32 v144, v144, v89, v90
	v_max3_f32 v144, v144, v91, v92
	v_max3_f32 v144, v144, v93, v94
	v_max3_f32 v144, v144, v95, v96
	v_max3_f32 v144, v144, v97, v66
	v_max3_f32 v144, v144, v67, v68
	v_max3_f32 v144, v144, v69, v70
	v_max3_f32 v144, v144, v71, v72
	v_max3_f32 v144, v144, v73, v74
	v_max3_f32 v144, v144, v75, v76
	v_max3_f32 v144, v144, v77, v78
	v_max3_f32 v144, v144, v79, v80
	v_max_f32_e32 v144, v144, v81
	v_mov_b32_e32 v160, v144
	s_nop 1
	v_permlane32_swap_b32_e32 v144, v160
	v_max_f32_e32 v144, v144, v160
	v_sub_f32_e32 v160, v144, v151
	v_cmp_ge_f32_e32 vcc, s18, v160
	s_cmp_eq_u64 vcc, exec
	s_cbranch_scc0 .Lmy_A_slow
	v_mov_b32_e32 v144, 1.0
